# U pass: partial-sum LDS read issued at step start instead of after the reduce; V pass: next-step expert-id LDS reads issued before the reduce instead of after the store
# baseline (speedup 1.0000x reference)
.Lux_skip1:
	s_add_i32 s101, s61, 0xffffff00
	s_and_b32 s101, s101, 0x700
	v_lshl_add_u32 v236, s101, 2, v190
	ds_read_b64 v[236:237], v236
	v_dot4c_i32_i8_e32 v138, v0, v64
	v_dot4c_i32_i8_e32 v178, v4, v64
	v_dot4c_i32_i8_e32 v185, v32, v64
	v_dot4c_i32_i8_e32 v186, v36, v64
	v_dot4c_i32_i8_e32 v138, v1, v65
	v_lshl_or_b32 v69, v69, 7, v137
	v_lshl_or_b32 v68, v68, 7, v174
	global_load_dwordx4 v[132:135], v68, s[14:15]
	global_load_dwordx4 v[128:131], v69, s[14:15]
	v_dot4c_i32_i8_e32 v178, v5, v65
	v_dot4c_i32_i8_e32 v185, v33, v65
	v_dot4c_i32_i8_e32 v186, v37, v65
	v_dot4c_i32_i8_e32 v138, v2, v66
	v_dot4c_i32_i8_e32 v178, v6, v66
	v_dot4c_i32_i8_e32 v185, v34, v66
	v_dot4c_i32_i8_e32 v186, v38, v66
	v_dot4c_i32_i8_e32 v138, v3, v67
	v_dot4c_i32_i8_e32 v178, v7, v67
	v_dot4c_i32_i8_e32 v185, v35, v67
	v_dot4c_i32_i8_e32 v186, v39, v67
	v_lshl_or_b32 v69, v70, 7, v174
	v_lshl_or_b32 v68, v71, 7, v137
	global_load_dwordx4 v[124:127], v69, s[14:15]
	global_load_dwordx4 v[120:123], v68, s[14:15]
	v_add_u32_dpp v215, v138, v138 row_ror:12 row_mask:0xf bank_mask:0x5
	v_add_u32_dpp v215, v185, v185 row_ror:4 row_mask:0xf bank_mask:0xa
	v_dot4_i32_i8 v180, v12, v64, 0
	v_dot4_i32_i8 v210, v44, v64, 0
	v_dot4c_i32_i8_e32 v180, v13, v65
	v_dot4_i32_i8 v181, v16, v64, 0
	v_lshl_or_b32 v69, v72, 7, v174
	v_lshl_or_b32 v68, v73, 7, v137
	global_load_dwordx4 v[116:119], v69, s[14:15]
	global_load_dwordx4 v[112:115], v68, s[14:15]
	v_dot4c_i32_i8_e32 v210, v45, v65
	v_dot4_i32_i8 v211, v48, v64, 0
	v_dot4c_i32_i8_e32 v180, v14, v66
	v_dot4c_i32_i8_e32 v181, v17, v65
	v_dot4c_i32_i8_e32 v210, v46, v66
	v_dot4c_i32_i8_e32 v211, v49, v65
	v_dot4c_i32_i8_e32 v180, v15, v67
	v_dot4c_i32_i8_e32 v181, v18, v66
	v_dot4c_i32_i8_e32 v210, v47, v67
	v_dot4c_i32_i8_e32 v211, v50, v66
	v_add_u32_dpp v178, v178, v178 row_ror:12 row_mask:0xf bank_mask:0x5
	v_add_u32_dpp v178, v186, v186 row_ror:4 row_mask:0xf bank_mask:0xa
	v_lshl_or_b32 v69, v74, 7, v174
	v_lshl_or_b32 v68, v75, 7, v137
	global_load_dwordx4 v[108:111], v69, s[14:15]
	global_load_dwordx4 v[104:107], v68, s[14:15]
	v_dot4c_i32_i8_e32 v181, v19, v67
	v_dot4c_i32_i8_e32 v211, v51, v67
	s_waitcnt lgkmcnt(0)
	v_add_u32_dpp v185, v180, v180 row_ror:12 row_mask:0xf bank_mask:0x5
	v_add_u32_dpp v185, v210, v210 row_ror:4 row_mask:0xf bank_mask:0xa
	v_dot4_i32_i8 v179, v8, v64, 0
	v_dot4_i32_i8 v182, v20, v64, 0
	v_lshl_or_b32 v69, v76, 7, v174
	v_lshl_or_b32 v68, v77, 7, v137
	global_load_dwordx4 v[100:103], v69, s[14:15]
	global_load_dwordx4 v[96:99], v68, s[14:15]
	v_dot4_i32_i8 v187, v40, v64, 0
	v_dot4_i32_i8 v212, v52, v64, 0
	v_dot4c_i32_i8_e32 v179, v9, v65
	v_dot4c_i32_i8_e32 v182, v21, v65
	v_dot4_i32_i8 v183, v24, v64, 0
	v_dot4c_i32_i8_e32 v187, v41, v65
	v_lshl_or_b32 v69, v78, 7, v174
	v_lshl_or_b32 v68, v79, 7, v137
	global_load_dwordx4 v[92:95], v69, s[14:15]
	global_load_dwordx4 v[88:91], v68, s[14:15]
	v_dot4c_i32_i8_e32 v212, v53, v65
	v_dot4_i32_i8 v213, v56, v64, 0
	v_dot4c_i32_i8_e32 v179, v10, v66
	v_dot4c_i32_i8_e32 v182, v22, v66
	v_dot4c_i32_i8_e32 v183, v25, v65
	v_dot4_i32_i8 v184, v28, v64, 0
	v_dot4c_i32_i8_e32 v187, v42, v66
	v_dot4c_i32_i8_e32 v212, v54, v66
	v_dot4c_i32_i8_e32 v213, v57, v65
	v_lshl_or_b32 v68, v81, 7, v137
	v_lshl_or_b32 v69, v80, 7, v174
	global_load_dwordx4 v[84:87], v69, s[14:15]
	global_load_dwordx4 v[76:79], v68, s[14:15]
	v_dot4_i32_i8 v214, v60, v64, 0
	v_dot4c_i32_i8_e32 v179, v11, v67
	v_dot4c_i32_i8_e32 v182, v23, v67
	v_dot4c_i32_i8_e32 v183, v26, v66
	v_dot4c_i32_i8_e32 v184, v29, v65
	v_dot4c_i32_i8_e32 v187, v43, v67
	v_dot4c_i32_i8_e32 v212, v55, v67
	v_dot4c_i32_i8_e32 v213, v58, v66
	v_dot4c_i32_i8_e32 v214, v61, v65
	v_dot4c_i32_i8_e32 v183, v27, v67
	v_dot4c_i32_i8_e32 v184, v30, v66
	v_dot4c_i32_i8_e32 v213, v59, v67
	v_lshl_or_b32 v68, v83, 7, v137
	v_lshl_or_b32 v69, v82, 7, v174
	global_load_dwordx4 v[72:75], v69, s[14:15]
	global_load_dwordx4 v[68:71], v68, s[14:15]
	v_add_u32_e32 v231, s99, v230
	ds_read_b128 v[80:83], v231
	v_dot4c_i32_i8_e32 v214, v62, v66
	v_add_u32_dpp v179, v179, v179 row_ror:12 row_mask:0xf bank_mask:0x5
	v_add_u32_dpp v179, v187, v187 row_ror:4 row_mask:0xf bank_mask:0xa
	v_dot4c_i32_i8_e32 v184, v31, v67
	v_dot4c_i32_i8_e32 v214, v63, v67
	s_waitcnt lgkmcnt(3)
	v_mov_b32_e32 v180, v185
	v_add_u32_dpp v181, v181, v181 row_ror:12 row_mask:0xf bank_mask:0x5
	v_add_u32_dpp v181, v211, v211 row_ror:4 row_mask:0xf bank_mask:0xa
	v_add_u32_dpp v185, v183, v183 row_ror:12 row_mask:0xf bank_mask:0x5
	v_add_u32_dpp v185, v213, v213 row_ror:4 row_mask:0xf bank_mask:0xa
	s_waitcnt lgkmcnt(3)
	v_add_u32_dpp v182, v182, v182 row_ror:12 row_mask:0xf bank_mask:0x5
	v_add_u32_dpp v182, v212, v212 row_ror:4 row_mask:0xf bank_mask:0xa
	s_waitcnt lgkmcnt(4)
	v_mov_b32_e32 v138, v215
	s_waitcnt lgkmcnt(3)
	s_waitcnt lgkmcnt(2)
	s_waitcnt lgkmcnt(1)
	v_mov_b32_e32 v183, v185
	v_add_u32_dpp v184, v184, v184 row_ror:12 row_mask:0xf bank_mask:0x5
	v_add_u32_dpp v184, v214, v214 row_ror:4 row_mask:0xf bank_mask:0xa
	v_add_u32_dpp v234, v138, v138 quad_perm:[2,3,0,1] row_mask:0xf bank_mask:0xf
	v_add_u32_dpp v235, v181, v181 quad_perm:[2,3,0,1] row_mask:0xf bank_mask:0xf
	v_cndmask_b32_e64 v138, v235, v234, s[4:5]
	v_add_u32_dpp v234, v178, v178 quad_perm:[2,3,0,1] row_mask:0xf bank_mask:0xf
	v_add_u32_dpp v235, v182, v182 quad_perm:[2,3,0,1] row_mask:0xf bank_mask:0xf
	v_cndmask_b32_e64 v181, v235, v234, s[4:5]
	s_waitcnt lgkmcnt(0)
	s_waitcnt lgkmcnt(3)
	v_add_u32_dpp v234, v179, v179 quad_perm:[2,3,0,1] row_mask:0xf bank_mask:0xf
	v_add_u32_dpp v235, v183, v183 quad_perm:[2,3,0,1] row_mask:0xf bank_mask:0xf
	v_cndmask_b32_e64 v178, v235, v234, s[4:5]
	s_waitcnt lgkmcnt(2)
	s_waitcnt lgkmcnt(1)
	v_add_u32_dpp v234, v180, v180 quad_perm:[2,3,0,1] row_mask:0xf bank_mask:0xf
	v_add_u32_dpp v235, v184, v184 quad_perm:[2,3,0,1] row_mask:0xf bank_mask:0xf
	v_cndmask_b32_e64 v179, v235, v234, s[4:5]
	s_waitcnt lgkmcnt(0)
	s_add_i32 s1, s61, 0xffffff00
	v_add_u32_dpp v234, v138, v138 quad_perm:[1,0,3,2] row_mask:0xf bank_mask:0xf
	v_add_u32_dpp v235, v178, v178 quad_perm:[1,0,3,2] row_mask:0xf bank_mask:0xf
	v_cndmask_b32_e64 v138, v235, v234, s[6:7]
	s_and_b32 s1, s1, 0x700
	s_waitcnt lgkmcnt(1)
	v_mov_b32_e32 v178, v138
	v_add_u32_dpp v234, v181, v181 quad_perm:[1,0,3,2] row_mask:0xf bank_mask:0xf
	v_add_u32_dpp v235, v179, v179 quad_perm:[1,0,3,2] row_mask:0xf bank_mask:0xf
	v_cndmask_b32_e64 v138, v235, v234, s[6:7]
	s_cmp_gt_u32 s0, 15
	s_waitcnt lgkmcnt(0)
	v_mov_b32_e32 v179, v138
	s_cselect_b64 s[14:15], -1, 0
	s_cmp_lt_u32 s0, 16
	v_lshl_add_u32 v138, s1, 2, v190
	s_cbranch_scc1 .LBB0_926
	s_waitcnt lgkmcnt(0)
	v_add_u32_e32 v178, v236, v178
	v_add_u32_e32 v179, v237, v179

.LBB0_928:
	v_lshl_add_u32 v238, s65, 2, v190
	ds_read_b64 v[238:239], v238
	s_waitcnt vmcnt(0)
	v_dot4_i32_i8 v138, v132, v80, 0
	global_load_dwordx4 v[0:3], v0, s[16:17]
	v_dot4_i32_i8 v132, v128, v80, 0
	v_dot4_i32_i8 v128, v124, v80, 0
	v_dot4_i32_i8 v124, v120, v80, 0
	global_load_dwordx4 v[4:7], v4, s[16:17]
	v_dot4_i32_i8 v120, v116, v80, 0
	v_dot4_i32_i8 v116, v112, v80, 0
	global_load_dwordx4 v[8:11], v8, s[16:17]
	v_dot4_i32_i8 v112, v108, v80, 0
	v_dot4_i32_i8 v108, v104, v80, 0
	v_dot4_i32_i8 v104, v100, v80, 0
	global_load_dwordx4 v[12:15], v12, s[16:17]
	v_dot4_i32_i8 v100, v96, v80, 0
	v_dot4_i32_i8 v96, v92, v80, 0
	v_dot4_i32_i8 v92, v88, v80, 0
	global_load_dwordx4 v[16:19], v16, s[16:17]
	v_dot4_i32_i8 v88, v84, v80, 0
	v_dot4c_i32_i8_e32 v138, v133, v81
	v_dot4c_i32_i8_e32 v104, v101, v81
	global_load_dwordx4 v[20:23], v20, s[16:17]
	v_dot4_i32_i8 v84, v76, v80, 0
	v_dot4c_i32_i8_e32 v138, v134, v82
	v_dot4c_i32_i8_e32 v132, v129, v81
	v_dot4c_i32_i8_e32 v104, v102, v82
	global_load_dwordx4 v[24:27], v24, s[16:17]
	v_dot4c_i32_i8_e32 v100, v97, v81
	v_dot4_i32_i8 v76, v72, v80, 0
	v_dot4c_i32_i8_e32 v138, v135, v83
	v_dot4c_i32_i8_e32 v132, v130, v82
	global_load_dwordx4 v[28:31], v28, s[16:17]
	v_dot4c_i32_i8_e32 v128, v125, v81
	v_dot4c_i32_i8_e32 v104, v103, v83
	v_dot4c_i32_i8_e32 v100, v98, v82
	v_dot4c_i32_i8_e32 v96, v93, v81
	v_dot4_i32_i8 v72, v68, v80, 0
	global_load_dwordx4 v[32:35], v32, s[16:17]
	v_dot4c_i32_i8_e32 v132, v131, v83
	v_dot4c_i32_i8_e32 v128, v126, v82
	v_dot4c_i32_i8_e32 v124, v121, v81
	v_dot4c_i32_i8_e32 v100, v99, v83
	v_dot4c_i32_i8_e32 v96, v94, v82
	global_load_dwordx4 v[36:39], v36, s[16:17]
	v_dot4c_i32_i8_e32 v92, v89, v81
	v_dot4c_i32_i8_e32 v72, v69, v81
	v_dot4c_i32_i8_e32 v128, v127, v83
	v_dot4c_i32_i8_e32 v124, v122, v82
	global_load_dwordx4 v[40:43], v40, s[16:17]
	v_dot4c_i32_i8_e32 v120, v117, v81
	v_dot4c_i32_i8_e32 v96, v95, v83
	v_dot4c_i32_i8_e32 v92, v90, v82
	v_dot4c_i32_i8_e32 v88, v85, v81
	v_dot4c_i32_i8_e32 v72, v70, v82
	global_load_dwordx4 v[44:47], v44, s[16:17]
	v_dot4c_i32_i8_e32 v124, v123, v83
	v_dot4c_i32_i8_e32 v120, v118, v82
	v_dot4c_i32_i8_e32 v116, v113, v81
	global_load_dwordx4 v[48:51], v48, s[16:17]
	v_dot4c_i32_i8_e32 v92, v91, v83
	v_dot4c_i32_i8_e32 v88, v86, v82
	v_dot4c_i32_i8_e32 v84, v77, v81
	v_dot4c_i32_i8_e32 v72, v71, v83
	global_load_dwordx4 v[52:55], v52, s[16:17]
	v_dot4c_i32_i8_e32 v120, v119, v83
	v_dot4c_i32_i8_e32 v116, v114, v82
	v_dot4c_i32_i8_e32 v88, v87, v83
	v_dot4c_i32_i8_e32 v84, v78, v82
	v_dot4c_i32_i8_e32 v76, v73, v81
	global_load_dwordx4 v[56:59], v56, s[16:17]
	v_dot4c_i32_i8_e32 v116, v115, v83
	v_dot4c_i32_i8_e32 v84, v79, v83
	v_dot4c_i32_i8_e32 v76, v74, v82
	global_load_dwordx4 v[60:63], v60, s[16:17]
	v_dot4c_i32_i8_e32 v76, v75, v83
	v_add_u32_dpp v68, v138, v138 row_ror:12 row_mask:0xf bank_mask:0x5
	v_add_u32_dpp v68, v104, v104 row_ror:4 row_mask:0xf bank_mask:0xa
	s_waitcnt lgkmcnt(4)
	v_add_u32_dpp v69, v132, v132 row_ror:12 row_mask:0xf bank_mask:0x5
	v_add_u32_dpp v69, v100, v100 row_ror:4 row_mask:0xf bank_mask:0xa
	s_waitcnt lgkmcnt(4)
	v_add_u32_dpp v70, v128, v128 row_ror:12 row_mask:0xf bank_mask:0x5
	v_add_u32_dpp v70, v96, v96 row_ror:4 row_mask:0xf bank_mask:0xa
	v_dot4c_i32_i8_e32 v112, v109, v81
	v_dot4c_i32_i8_e32 v108, v105, v81
	s_waitcnt lgkmcnt(3)
	v_add_u32_dpp v71, v124, v124 row_ror:12 row_mask:0xf bank_mask:0x5
	v_add_u32_dpp v71, v92, v92 row_ror:4 row_mask:0xf bank_mask:0xa
	v_dot4c_i32_i8_e32 v112, v110, v82
	v_dot4c_i32_i8_e32 v108, v106, v82
	s_waitcnt lgkmcnt(2)
	v_add_u32_dpp v73, v120, v120 row_ror:12 row_mask:0xf bank_mask:0x5
	v_add_u32_dpp v73, v88, v88 row_ror:4 row_mask:0xf bank_mask:0xa
	v_dot4c_i32_i8_e32 v112, v111, v83
	v_dot4c_i32_i8_e32 v108, v107, v83
	s_waitcnt lgkmcnt(1)
	v_add_u32_dpp v74, v116, v116 row_ror:12 row_mask:0xf bank_mask:0x5
	v_add_u32_dpp v74, v84, v84 row_ror:4 row_mask:0xf bank_mask:0xa
	s_waitcnt lgkmcnt(0)
	v_add_u32_dpp v75, v112, v112 row_ror:12 row_mask:0xf bank_mask:0x5
	v_add_u32_dpp v75, v76, v76 row_ror:4 row_mask:0xf bank_mask:0xa
	v_add_u32_dpp v72, v72, v72 row_ror:4 row_mask:0xf bank_mask:0xa
	v_add_u32_dpp v72, v108, v108 row_ror:12 row_mask:0xf bank_mask:0x5
	v_add_u32_dpp v234, v68, v68 quad_perm:[2,3,0,1] row_mask:0xf bank_mask:0xf
	v_add_u32_dpp v235, v73, v73 quad_perm:[2,3,0,1] row_mask:0xf bank_mask:0xf
	v_cndmask_b32_e64 v68, v235, v234, s[4:5]
	s_waitcnt lgkmcnt(1)
	s_waitcnt lgkmcnt(0)
	v_add_u32_dpp v234, v69, v69 quad_perm:[2,3,0,1] row_mask:0xf bank_mask:0xf
	v_add_u32_dpp v235, v74, v74 quad_perm:[2,3,0,1] row_mask:0xf bank_mask:0xf
	v_cndmask_b32_e64 v73, v235, v234, s[4:5]
	v_add_u32_dpp v234, v70, v70 quad_perm:[2,3,0,1] row_mask:0xf bank_mask:0xf
	v_add_u32_dpp v235, v75, v75 quad_perm:[2,3,0,1] row_mask:0xf bank_mask:0xf
	v_cndmask_b32_e64 v70, v235, v234, s[4:5]
	v_add_u32_dpp v234, v71, v71 quad_perm:[2,3,0,1] row_mask:0xf bank_mask:0xf
	v_add_u32_dpp v235, v72, v72 quad_perm:[2,3,0,1] row_mask:0xf bank_mask:0xf
	v_cndmask_b32_e64 v71, v235, v234, s[4:5]
	s_waitcnt lgkmcnt(3)
	s_waitcnt lgkmcnt(2)
	v_mov_b32_e32 v69, v73
	s_waitcnt lgkmcnt(1)
	s_waitcnt lgkmcnt(0)
	v_add_u32_dpp v234, v68, v68 quad_perm:[1,0,3,2] row_mask:0xf bank_mask:0xf
	v_add_u32_dpp v235, v70, v70 quad_perm:[1,0,3,2] row_mask:0xf bank_mask:0xf
	v_cndmask_b32_e64 v68, v235, v234, s[6:7]
	v_add_u32_dpp v234, v69, v69 quad_perm:[1,0,3,2] row_mask:0xf bank_mask:0xf
	v_add_u32_dpp v235, v71, v71 quad_perm:[1,0,3,2] row_mask:0xf bank_mask:0xf
	v_cndmask_b32_e64 v69, v235, v234, s[6:7]
	s_andn2_b64 vcc, exec, s[14:15]
	s_waitcnt lgkmcnt(1)
	s_waitcnt lgkmcnt(0)
	v_lshl_add_u32 v70, s65, 2, v190
	s_cbranch_vccnz .LBB0_923
	s_waitcnt lgkmcnt(0)
	v_add_u32_e32 v68, v238, v68
	v_add_u32_e32 v69, v239, v69
	s_branch .LBB0_923

.LBB0_934:
	s_add_i32 s15, s17, 0xffffff80
	s_and_b32 s15, s15, 0x780
	v_lshl_add_u32 v76, s15, 2, v189
	ds_read_b128 v[64:67], v76
	s_add_i32 s14, s34, 0xfffc0000
	s_add_i32 s1, s0, 1
	s_and_b32 s14, s14, 0x1e00000
	s_add_u32 s14, s38, s14
	s_waitcnt lgkmcnt(0)
	s_addc_u32 s15, s39, 0
	ds_read_b128 v[68:71], v76 offset:16
	ds_read_b128 v[72:75], v76 offset:32
	ds_read_b128 v[128:131], v76 offset:48
	v_lshl_or_b32 v65, v65, 7, v137
	v_lshl_or_b32 v64, v64, 7, v174
	global_load_dwordx4 v[124:127], v64, s[14:15]
	global_load_dwordx4 v[120:123], v65, s[14:15]
	v_lshl_or_b32 v64, v67, 7, v137
	v_lshl_or_b32 v65, v66, 7, v174
	global_load_dwordx4 v[116:119], v65, s[14:15]
	global_load_dwordx4 v[112:115], v64, s[14:15]
	s_waitcnt lgkmcnt(2)
	v_lshl_or_b32 v64, v69, 7, v137
	v_lshl_or_b32 v65, v68, 7, v174
	global_load_dwordx4 v[108:111], v65, s[14:15]
	global_load_dwordx4 v[104:107], v64, s[14:15]
	v_lshl_or_b32 v64, v71, 7, v137
	v_lshl_or_b32 v65, v70, 7, v174
	global_load_dwordx4 v[100:103], v65, s[14:15]
	global_load_dwordx4 v[96:99], v64, s[14:15]
	s_waitcnt lgkmcnt(1)
	v_lshl_or_b32 v64, v73, 7, v137
	v_lshl_or_b32 v65, v72, 7, v174
	global_load_dwordx4 v[92:95], v65, s[14:15]
	global_load_dwordx4 v[88:91], v64, s[14:15]
	s_and_b32 s59, s1, 15
	v_lshl_or_b32 v64, v75, 7, v137
	v_lshl_or_b32 v65, v74, 7, v174
	s_add_i32 s1, s16, -16
	v_or_b32_e32 v186, s59, v176
	global_load_dwordx4 v[84:87], v65, s[14:15]
	global_load_dwordx4 v[80:83], v64, s[14:15]
	s_waitcnt lgkmcnt(0)
	s_and_b32 s1, s1, 0x780
	v_ashrrev_i32_e32 v187, 31, v186
	v_lshl_or_b32 v64, v129, 7, v137
	v_lshl_or_b32 v65, v128, 7, v174
	v_or_b32_e32 v214, s1, v192
	global_load_dwordx4 v[76:79], v65, s[14:15]
	global_load_dwordx4 v[72:75], v64, s[14:15]
	v_lshlrev_b32_e32 v64, 7, v131
	v_lshlrev_b32_e32 v65, 7, v130
	v_or_b32_e32 v64, v64, v137
	v_or_b32_e32 v65, v65, v174
	s_and_b32 s1, s0, 14
	s_waitcnt vmcnt(30)
	v_cvt_pk_f32_fp8_e32 v[224:225], v0
	v_cvt_pk_f32_fp8_sdwa v[226:227], v0 src0_sel:WORD_1
	v_cvt_pk_f32_fp8_e32 v[228:229], v1
	v_cvt_pk_f32_fp8_sdwa v[230:231], v1 src0_sel:WORD_1
	global_load_dwordx4 v[68:71], v65, s[14:15]
	s_nop 0
	global_load_dwordx4 v[64:67], v64, s[14:15]
	v_lshl_add_u32 v128, s1, 9, v193
	s_waitcnt vmcnt(31)
	v_cvt_pk_f32_fp8_e32 v[240:241], v4
	v_cvt_pk_f32_fp8_sdwa v[242:243], v4 src0_sel:WORD_1
	v_cvt_pk_f32_fp8_e32 v[244:245], v5
	v_cvt_pk_f32_fp8_sdwa v[246:247], v5 src0_sel:WORD_1
	ds_read_b128 v[216:219], v128
	ds_read_b128 v[220:223], v128 offset:16
	ds_read_b128 v[132:135], v128 offset:32
	ds_read_b128 v[128:131], v128 offset:48
	v_cvt_pk_f32_fp8_e32 v[232:233], v2
	s_waitcnt lgkmcnt(3)
	v_pk_fma_f32 v[224:225], v[216:217], v[224:225], 0 op_sel_hi:[0,1,0]
	v_pk_fma_f32 v[226:227], v[216:217], v[226:227], 0 op_sel_hi:[0,1,0]
	v_pk_fma_f32 v[228:229], v[216:217], v[228:229], 0 op_sel_hi:[0,1,0]
	v_pk_fma_f32 v[230:231], v[216:217], v[230:231], 0 op_sel_hi:[0,1,0]
	v_cvt_pk_f32_fp8_sdwa v[234:235], v2 src0_sel:WORD_1
	v_cvt_pk_f32_fp8_e32 v[236:237], v3
	v_cvt_pk_f32_fp8_sdwa v[238:239], v3 src0_sel:WORD_1
	v_pk_fma_f32 v[224:225], v[216:217], v[240:241], v[224:225] op_sel:[1,0,0]
	v_pk_fma_f32 v[226:227], v[216:217], v[242:243], v[226:227] op_sel:[1,0,0]
	v_pk_fma_f32 v[228:229], v[216:217], v[244:245], v[228:229] op_sel:[1,0,0]
	v_pk_fma_f32 v[230:231], v[216:217], v[246:247], v[230:231] op_sel:[1,0,0]
	v_cvt_pk_f32_fp8_e32 v[240:241], v6
	v_cvt_pk_f32_fp8_sdwa v[242:243], v6 src0_sel:WORD_1
	v_cvt_pk_f32_fp8_e32 v[244:245], v7
	v_cvt_pk_f32_fp8_sdwa v[246:247], v7 src0_sel:WORD_1
	v_pk_fma_f32 v[232:233], v[216:217], v[232:233], 0 op_sel_hi:[0,1,0]
	v_pk_fma_f32 v[234:235], v[216:217], v[234:235], 0 op_sel_hi:[0,1,0]
	v_pk_fma_f32 v[236:237], v[216:217], v[236:237], 0 op_sel_hi:[0,1,0]
	v_pk_fma_f32 v[238:239], v[216:217], v[238:239], 0 op_sel_hi:[0,1,0]
	v_pk_fma_f32 v[232:233], v[216:217], v[240:241], v[232:233] op_sel:[1,0,0]
	v_pk_fma_f32 v[234:235], v[216:217], v[242:243], v[234:235] op_sel:[1,0,0]
	v_pk_fma_f32 v[236:237], v[216:217], v[244:245], v[236:237] op_sel:[1,0,0]
	v_pk_fma_f32 v[216:217], v[216:217], v[246:247], v[238:239] op_sel:[1,0,0]
	s_waitcnt vmcnt(30)
	v_cvt_pk_f32_fp8_e32 v[238:239], v8
	v_cvt_pk_f32_fp8_sdwa v[240:241], v8 src0_sel:WORD_1
	v_cvt_pk_f32_fp8_e32 v[242:243], v9
	v_cvt_pk_f32_fp8_sdwa v[244:245], v9 src0_sel:WORD_1
	v_pk_fma_f32 v[224:225], v[218:219], v[238:239], v[224:225] op_sel_hi:[0,1,1]
	v_pk_fma_f32 v[226:227], v[218:219], v[240:241], v[226:227] op_sel_hi:[0,1,1]
	v_pk_fma_f32 v[228:229], v[218:219], v[242:243], v[228:229] op_sel_hi:[0,1,1]
	v_pk_fma_f32 v[230:231], v[218:219], v[244:245], v[230:231] op_sel_hi:[0,1,1]
	v_cvt_pk_f32_fp8_e32 v[238:239], v10
	v_cvt_pk_f32_fp8_sdwa v[240:241], v10 src0_sel:WORD_1
	v_cvt_pk_f32_fp8_e32 v[242:243], v11
	v_cvt_pk_f32_fp8_sdwa v[244:245], v11 src0_sel:WORD_1
	v_pk_fma_f32 v[232:233], v[218:219], v[238:239], v[232:233] op_sel_hi:[0,1,1]
	v_pk_fma_f32 v[234:235], v[218:219], v[240:241], v[234:235] op_sel_hi:[0,1,1]
	v_pk_fma_f32 v[236:237], v[218:219], v[242:243], v[236:237] op_sel_hi:[0,1,1]
	v_pk_fma_f32 v[216:217], v[218:219], v[244:245], v[216:217] op_sel_hi:[0,1,1]
	v_mov_b32_e32 v138, v219
	s_waitcnt vmcnt(29)
	v_cvt_pk_f32_fp8_e32 v[218:219], v12
	v_cvt_pk_f32_fp8_sdwa v[238:239], v12 src0_sel:WORD_1
	v_cvt_pk_f32_fp8_e32 v[240:241], v13
	v_cvt_pk_f32_fp8_sdwa v[242:243], v13 src0_sel:WORD_1
	v_pk_fma_f32 v[218:219], v[138:139], v[218:219], v[224:225] op_sel_hi:[0,1,1]
	v_pk_fma_f32 v[224:225], v[138:139], v[238:239], v[226:227] op_sel_hi:[0,1,1]
	v_pk_fma_f32 v[226:227], v[138:139], v[240:241], v[228:229] op_sel_hi:[0,1,1]
	v_pk_fma_f32 v[228:229], v[138:139], v[242:243], v[230:231] op_sel_hi:[0,1,1]
	v_cvt_pk_f32_fp8_e32 v[230:231], v14
	v_cvt_pk_f32_fp8_sdwa v[238:239], v14 src0_sel:WORD_1
	v_cvt_pk_f32_fp8_e32 v[240:241], v15
	v_cvt_pk_f32_fp8_sdwa v[242:243], v15 src0_sel:WORD_1
	v_pk_fma_f32 v[230:231], v[138:139], v[230:231], v[232:233] op_sel_hi:[0,1,1]
	v_pk_fma_f32 v[232:233], v[138:139], v[238:239], v[234:235] op_sel_hi:[0,1,1]
	v_pk_fma_f32 v[234:235], v[138:139], v[240:241], v[236:237] op_sel_hi:[0,1,1]
	v_pk_fma_f32 v[216:217], v[138:139], v[242:243], v[216:217] op_sel_hi:[0,1,1]
	s_waitcnt vmcnt(28)
	v_cvt_pk_f32_fp8_e32 v[236:237], v16
	v_cvt_pk_f32_fp8_sdwa v[238:239], v16 src0_sel:WORD_1
	v_cvt_pk_f32_fp8_e32 v[240:241], v17
	v_cvt_pk_f32_fp8_sdwa v[242:243], v17 src0_sel:WORD_1
	s_waitcnt lgkmcnt(2)
	v_pk_fma_f32 v[218:219], v[220:221], v[236:237], v[218:219] op_sel_hi:[0,1,1]
	v_pk_fma_f32 v[224:225], v[220:221], v[238:239], v[224:225] op_sel_hi:[0,1,1]
	v_pk_fma_f32 v[226:227], v[220:221], v[240:241], v[226:227] op_sel_hi:[0,1,1]
	v_pk_fma_f32 v[228:229], v[220:221], v[242:243], v[228:229] op_sel_hi:[0,1,1]
	v_cvt_pk_f32_fp8_e32 v[236:237], v18
	v_cvt_pk_f32_fp8_sdwa v[238:239], v18 src0_sel:WORD_1
	v_cvt_pk_f32_fp8_e32 v[240:241], v19
	v_cvt_pk_f32_fp8_sdwa v[242:243], v19 src0_sel:WORD_1
	v_pk_fma_f32 v[230:231], v[220:221], v[236:237], v[230:231] op_sel_hi:[0,1,1]
	v_pk_fma_f32 v[232:233], v[220:221], v[238:239], v[232:233] op_sel_hi:[0,1,1]
	v_pk_fma_f32 v[234:235], v[220:221], v[240:241], v[234:235] op_sel_hi:[0,1,1]
	v_pk_fma_f32 v[216:217], v[220:221], v[242:243], v[216:217] op_sel_hi:[0,1,1]
	s_waitcnt vmcnt(27)
	v_cvt_pk_f32_fp8_e32 v[236:237], v20
	v_cvt_pk_f32_fp8_sdwa v[238:239], v20 src0_sel:WORD_1
	v_cvt_pk_f32_fp8_e32 v[240:241], v21
	v_cvt_pk_f32_fp8_sdwa v[242:243], v21 src0_sel:WORD_1
	v_pk_fma_f32 v[218:219], v[220:221], v[236:237], v[218:219] op_sel:[1,0,0]
	v_pk_fma_f32 v[224:225], v[220:221], v[238:239], v[224:225] op_sel:[1,0,0]
	v_pk_fma_f32 v[226:227], v[220:221], v[240:241], v[226:227] op_sel:[1,0,0]
	v_pk_fma_f32 v[228:229], v[220:221], v[242:243], v[228:229] op_sel:[1,0,0]
	v_cvt_pk_f32_fp8_e32 v[236:237], v22
	v_cvt_pk_f32_fp8_sdwa v[238:239], v22 src0_sel:WORD_1
	v_cvt_pk_f32_fp8_e32 v[240:241], v23
	v_cvt_pk_f32_fp8_sdwa v[242:243], v23 src0_sel:WORD_1
	v_pk_fma_f32 v[230:231], v[220:221], v[236:237], v[230:231] op_sel:[1,0,0]
	v_pk_fma_f32 v[232:233], v[220:221], v[238:239], v[232:233] op_sel:[1,0,0]
	v_pk_fma_f32 v[234:235], v[220:221], v[240:241], v[234:235] op_sel:[1,0,0]
	v_pk_fma_f32 v[216:217], v[220:221], v[242:243], v[216:217] op_sel:[1,0,0]
	s_waitcnt vmcnt(26)
	v_cvt_pk_f32_fp8_e32 v[220:221], v24
	v_cvt_pk_f32_fp8_sdwa v[236:237], v24 src0_sel:WORD_1
	v_cvt_pk_f32_fp8_e32 v[238:239], v25
	v_cvt_pk_f32_fp8_sdwa v[240:241], v25 src0_sel:WORD_1
	v_pk_fma_f32 v[218:219], v[222:223], v[220:221], v[218:219] op_sel_hi:[0,1,1]
	v_pk_fma_f32 v[220:221], v[222:223], v[236:237], v[224:225] op_sel_hi:[0,1,1]
	v_pk_fma_f32 v[224:225], v[222:223], v[238:239], v[226:227] op_sel_hi:[0,1,1]
	v_pk_fma_f32 v[226:227], v[222:223], v[240:241], v[228:229] op_sel_hi:[0,1,1]
	v_cvt_pk_f32_fp8_e32 v[228:229], v26
	v_cvt_pk_f32_fp8_sdwa v[236:237], v26 src0_sel:WORD_1
	v_cvt_pk_f32_fp8_e32 v[238:239], v27
	v_cvt_pk_f32_fp8_sdwa v[240:241], v27 src0_sel:WORD_1
	v_pk_fma_f32 v[228:229], v[222:223], v[228:229], v[230:231] op_sel_hi:[0,1,1]
	v_pk_fma_f32 v[230:231], v[222:223], v[236:237], v[232:233] op_sel_hi:[0,1,1]
	v_pk_fma_f32 v[232:233], v[222:223], v[238:239], v[234:235] op_sel_hi:[0,1,1]
	v_pk_fma_f32 v[216:217], v[222:223], v[240:241], v[216:217] op_sel_hi:[0,1,1]
	v_mov_b32_e32 v138, v223
	s_waitcnt vmcnt(25)
	v_cvt_pk_f32_fp8_e32 v[222:223], v28
	v_cvt_pk_f32_fp8_sdwa v[234:235], v28 src0_sel:WORD_1
	v_cvt_pk_f32_fp8_e32 v[236:237], v29
	v_cvt_pk_f32_fp8_sdwa v[238:239], v29 src0_sel:WORD_1
	v_pk_fma_f32 v[218:219], v[138:139], v[222:223], v[218:219] op_sel_hi:[0,1,1]
	v_pk_fma_f32 v[220:221], v[138:139], v[234:235], v[220:221] op_sel_hi:[0,1,1]
	v_pk_fma_f32 v[222:223], v[138:139], v[236:237], v[224:225] op_sel_hi:[0,1,1]
	v_pk_fma_f32 v[224:225], v[138:139], v[238:239], v[226:227] op_sel_hi:[0,1,1]
	v_cvt_pk_f32_fp8_e32 v[226:227], v30
	v_cvt_pk_f32_fp8_sdwa v[234:235], v30 src0_sel:WORD_1
	v_cvt_pk_f32_fp8_e32 v[236:237], v31
	v_cvt_pk_f32_fp8_sdwa v[238:239], v31 src0_sel:WORD_1
	v_pk_fma_f32 v[226:227], v[138:139], v[226:227], v[228:229] op_sel_hi:[0,1,1]
	v_pk_fma_f32 v[228:229], v[138:139], v[234:235], v[230:231] op_sel_hi:[0,1,1]
	v_pk_fma_f32 v[230:231], v[138:139], v[236:237], v[232:233] op_sel_hi:[0,1,1]
	v_pk_fma_f32 v[216:217], v[138:139], v[238:239], v[216:217] op_sel_hi:[0,1,1]
	s_waitcnt vmcnt(24)
	v_cvt_pk_f32_fp8_e32 v[232:233], v32
	v_cvt_pk_f32_fp8_sdwa v[234:235], v32 src0_sel:WORD_1
	v_cvt_pk_f32_fp8_e32 v[236:237], v33
	v_cvt_pk_f32_fp8_sdwa v[238:239], v33 src0_sel:WORD_1
	s_waitcnt lgkmcnt(1)
	v_pk_fma_f32 v[218:219], v[132:133], v[232:233], v[218:219] op_sel_hi:[0,1,1]
	v_pk_fma_f32 v[220:221], v[132:133], v[234:235], v[220:221] op_sel_hi:[0,1,1]
	v_pk_fma_f32 v[222:223], v[132:133], v[236:237], v[222:223] op_sel_hi:[0,1,1]
	v_pk_fma_f32 v[224:225], v[132:133], v[238:239], v[224:225] op_sel_hi:[0,1,1]
	v_cvt_pk_f32_fp8_e32 v[232:233], v34
	v_cvt_pk_f32_fp8_sdwa v[234:235], v34 src0_sel:WORD_1
	v_cvt_pk_f32_fp8_e32 v[236:237], v35
	v_cvt_pk_f32_fp8_sdwa v[238:239], v35 src0_sel:WORD_1
	v_pk_fma_f32 v[226:227], v[132:133], v[232:233], v[226:227] op_sel_hi:[0,1,1]
	v_pk_fma_f32 v[228:229], v[132:133], v[234:235], v[228:229] op_sel_hi:[0,1,1]
	v_pk_fma_f32 v[230:231], v[132:133], v[236:237], v[230:231] op_sel_hi:[0,1,1]
	v_pk_fma_f32 v[216:217], v[132:133], v[238:239], v[216:217] op_sel_hi:[0,1,1]
	s_waitcnt vmcnt(23)
	v_cvt_pk_f32_fp8_e32 v[232:233], v36
	v_cvt_pk_f32_fp8_sdwa v[234:235], v36 src0_sel:WORD_1
	v_cvt_pk_f32_fp8_e32 v[236:237], v37
	v_cvt_pk_f32_fp8_sdwa v[238:239], v37 src0_sel:WORD_1
	v_pk_fma_f32 v[218:219], v[132:133], v[232:233], v[218:219] op_sel:[1,0,0]
	v_pk_fma_f32 v[220:221], v[132:133], v[234:235], v[220:221] op_sel:[1,0,0]
	v_pk_fma_f32 v[222:223], v[132:133], v[236:237], v[222:223] op_sel:[1,0,0]
	v_pk_fma_f32 v[224:225], v[132:133], v[238:239], v[224:225] op_sel:[1,0,0]
	v_cvt_pk_f32_fp8_e32 v[232:233], v38
	v_cvt_pk_f32_fp8_sdwa v[234:235], v38 src0_sel:WORD_1
	v_cvt_pk_f32_fp8_e32 v[236:237], v39
	v_cvt_pk_f32_fp8_sdwa v[238:239], v39 src0_sel:WORD_1
	v_pk_fma_f32 v[226:227], v[132:133], v[232:233], v[226:227] op_sel:[1,0,0]
	v_pk_fma_f32 v[228:229], v[132:133], v[234:235], v[228:229] op_sel:[1,0,0]
	v_pk_fma_f32 v[230:231], v[132:133], v[236:237], v[230:231] op_sel:[1,0,0]
	v_pk_fma_f32 v[132:133], v[132:133], v[238:239], v[216:217] op_sel:[1,0,0]
	s_waitcnt vmcnt(22)
	v_cvt_pk_f32_fp8_e32 v[216:217], v40
	v_cvt_pk_f32_fp8_sdwa v[232:233], v40 src0_sel:WORD_1
	v_cvt_pk_f32_fp8_e32 v[234:235], v41
	v_cvt_pk_f32_fp8_sdwa v[236:237], v41 src0_sel:WORD_1
	v_pk_fma_f32 v[216:217], v[134:135], v[216:217], v[218:219] op_sel_hi:[0,1,1]
	v_pk_fma_f32 v[218:219], v[134:135], v[232:233], v[220:221] op_sel_hi:[0,1,1]
	v_pk_fma_f32 v[220:221], v[134:135], v[234:235], v[222:223] op_sel_hi:[0,1,1]
	v_pk_fma_f32 v[222:223], v[134:135], v[236:237], v[224:225] op_sel_hi:[0,1,1]
	v_cvt_pk_f32_fp8_e32 v[224:225], v42
	v_cvt_pk_f32_fp8_sdwa v[232:233], v42 src0_sel:WORD_1
	v_cvt_pk_f32_fp8_e32 v[234:235], v43
	v_cvt_pk_f32_fp8_sdwa v[236:237], v43 src0_sel:WORD_1
	v_pk_fma_f32 v[224:225], v[134:135], v[224:225], v[226:227] op_sel_hi:[0,1,1]
	v_pk_fma_f32 v[226:227], v[134:135], v[232:233], v[228:229] op_sel_hi:[0,1,1]
	v_pk_fma_f32 v[228:229], v[134:135], v[234:235], v[230:231] op_sel_hi:[0,1,1]
	v_pk_fma_f32 v[132:133], v[134:135], v[236:237], v[132:133] op_sel_hi:[0,1,1]
	s_waitcnt vmcnt(21)
	v_cvt_pk_f32_fp8_e32 v[230:231], v44
	v_cvt_pk_f32_fp8_sdwa v[232:233], v44 src0_sel:WORD_1
	v_cvt_pk_f32_fp8_e32 v[234:235], v45
	v_cvt_pk_f32_fp8_sdwa v[236:237], v45 src0_sel:WORD_1
	v_mov_b32_e32 v134, v135
	v_pk_fma_f32 v[216:217], v[134:135], v[230:231], v[216:217] op_sel_hi:[0,1,1]
	v_pk_fma_f32 v[218:219], v[134:135], v[232:233], v[218:219] op_sel_hi:[0,1,1]
	v_pk_fma_f32 v[220:221], v[134:135], v[234:235], v[220:221] op_sel_hi:[0,1,1]
	v_pk_fma_f32 v[222:223], v[134:135], v[236:237], v[222:223] op_sel_hi:[0,1,1]
	v_cvt_pk_f32_fp8_e32 v[230:231], v46
	v_cvt_pk_f32_fp8_sdwa v[232:233], v46 src0_sel:WORD_1
	v_cvt_pk_f32_fp8_e32 v[234:235], v47
	v_cvt_pk_f32_fp8_sdwa v[236:237], v47 src0_sel:WORD_1
	v_pk_fma_f32 v[224:225], v[134:135], v[230:231], v[224:225] op_sel_hi:[0,1,1]
	v_pk_fma_f32 v[226:227], v[134:135], v[232:233], v[226:227] op_sel_hi:[0,1,1]
	v_pk_fma_f32 v[228:229], v[134:135], v[234:235], v[228:229] op_sel_hi:[0,1,1]
	v_pk_fma_f32 v[132:133], v[134:135], v[236:237], v[132:133] op_sel_hi:[0,1,1]
	s_waitcnt vmcnt(20)
	v_cvt_pk_f32_fp8_e32 v[134:135], v48
	v_cvt_pk_f32_fp8_sdwa v[230:231], v48 src0_sel:WORD_1
	v_cvt_pk_f32_fp8_e32 v[232:233], v49
	v_cvt_pk_f32_fp8_sdwa v[234:235], v49 src0_sel:WORD_1
	s_waitcnt lgkmcnt(0)
	v_pk_fma_f32 v[134:135], v[128:129], v[134:135], v[216:217] op_sel_hi:[0,1,1]
	v_pk_fma_f32 v[216:217], v[128:129], v[230:231], v[218:219] op_sel_hi:[0,1,1]
	v_pk_fma_f32 v[218:219], v[128:129], v[232:233], v[220:221] op_sel_hi:[0,1,1]
	v_pk_fma_f32 v[220:221], v[128:129], v[234:235], v[222:223] op_sel_hi:[0,1,1]
	v_cvt_pk_f32_fp8_e32 v[222:223], v50
	v_cvt_pk_f32_fp8_sdwa v[230:231], v50 src0_sel:WORD_1
	v_cvt_pk_f32_fp8_e32 v[232:233], v51
	v_cvt_pk_f32_fp8_sdwa v[234:235], v51 src0_sel:WORD_1
	v_pk_fma_f32 v[222:223], v[128:129], v[222:223], v[224:225] op_sel_hi:[0,1,1]
	v_pk_fma_f32 v[224:225], v[128:129], v[230:231], v[226:227] op_sel_hi:[0,1,1]
	v_pk_fma_f32 v[226:227], v[128:129], v[232:233], v[228:229] op_sel_hi:[0,1,1]
	v_pk_fma_f32 v[132:133], v[128:129], v[234:235], v[132:133] op_sel_hi:[0,1,1]
	s_waitcnt vmcnt(19)
	v_cvt_pk_f32_fp8_e32 v[228:229], v52
	v_cvt_pk_f32_fp8_sdwa v[230:231], v52 src0_sel:WORD_1
	v_cvt_pk_f32_fp8_e32 v[232:233], v53
	v_cvt_pk_f32_fp8_sdwa v[234:235], v53 src0_sel:WORD_1
	v_pk_fma_f32 v[134:135], v[128:129], v[228:229], v[134:135] op_sel:[1,0,0]
	v_pk_fma_f32 v[216:217], v[128:129], v[230:231], v[216:217] op_sel:[1,0,0]
	v_pk_fma_f32 v[218:219], v[128:129], v[232:233], v[218:219] op_sel:[1,0,0]
	v_pk_fma_f32 v[220:221], v[128:129], v[234:235], v[220:221] op_sel:[1,0,0]
	v_cvt_pk_f32_fp8_e32 v[228:229], v54
	v_cvt_pk_f32_fp8_sdwa v[230:231], v54 src0_sel:WORD_1
	v_cvt_pk_f32_fp8_e32 v[232:233], v55
	v_cvt_pk_f32_fp8_sdwa v[234:235], v55 src0_sel:WORD_1
	v_pk_fma_f32 v[222:223], v[128:129], v[228:229], v[222:223] op_sel:[1,0,0]
	v_pk_fma_f32 v[224:225], v[128:129], v[230:231], v[224:225] op_sel:[1,0,0]
	v_pk_fma_f32 v[226:227], v[128:129], v[232:233], v[226:227] op_sel:[1,0,0]
	v_pk_fma_f32 v[128:129], v[128:129], v[234:235], v[132:133] op_sel:[1,0,0]
	s_waitcnt vmcnt(18)
	v_cvt_pk_f32_fp8_e32 v[132:133], v56
	v_cvt_pk_f32_fp8_sdwa v[228:229], v56 src0_sel:WORD_1
	v_cvt_pk_f32_fp8_e32 v[230:231], v57
	v_cvt_pk_f32_fp8_sdwa v[232:233], v57 src0_sel:WORD_1
	v_pk_fma_f32 v[132:133], v[130:131], v[132:133], v[134:135] op_sel_hi:[0,1,1]
	v_pk_fma_f32 v[134:135], v[130:131], v[228:229], v[216:217] op_sel_hi:[0,1,1]
	v_pk_fma_f32 v[216:217], v[130:131], v[230:231], v[218:219] op_sel_hi:[0,1,1]
	v_pk_fma_f32 v[218:219], v[130:131], v[232:233], v[220:221] op_sel_hi:[0,1,1]
	v_cvt_pk_f32_fp8_e32 v[220:221], v58
	v_cvt_pk_f32_fp8_sdwa v[228:229], v58 src0_sel:WORD_1
	v_cvt_pk_f32_fp8_e32 v[230:231], v59
	v_cvt_pk_f32_fp8_sdwa v[232:233], v59 src0_sel:WORD_1
	v_pk_fma_f32 v[220:221], v[130:131], v[220:221], v[222:223] op_sel_hi:[0,1,1]
	v_pk_fma_f32 v[222:223], v[130:131], v[228:229], v[224:225] op_sel_hi:[0,1,1]
	s_waitcnt vmcnt(17)
	s_and_b32 s101, s1, 3
	v_lshl_add_u32 v253, s101, 8, v252
	ds_read_b32 v210, v253
	ds_read_b32 v211, v253 offset:1024
	v_cvt_pk_f32_fp8_sdwa v[228:229], v60 src0_sel:WORD_1
	v_pk_fma_f32 v[224:225], v[130:131], v[230:231], v[226:227] op_sel_hi:[0,1,1]
	v_cvt_pk_f32_fp8_e32 v[226:227], v60
	v_cvt_pk_f32_fp8_e32 v[230:231], v61
	v_pk_fma_f32 v[128:129], v[130:131], v[232:233], v[128:129] op_sel_hi:[0,1,1]
	v_mov_b32_e32 v130, v131
	v_cvt_pk_f32_fp8_sdwa v[232:233], v61 src0_sel:WORD_1
	v_pk_fma_f32 v[134:135], v[130:131], v[228:229], v[134:135] op_sel_hi:[0,1,1]
	v_cvt_pk_f32_fp8_sdwa v[228:229], v62 src0_sel:WORD_1
	v_pk_fma_f32 v[132:133], v[130:131], v[226:227], v[132:133] op_sel_hi:[0,1,1]
	v_pk_fma_f32 v[216:217], v[130:131], v[230:231], v[216:217] op_sel_hi:[0,1,1]
	v_cvt_pk_f32_fp8_e32 v[226:227], v62
	v_cvt_pk_f32_fp8_e32 v[230:231], v63
	v_pk_fma_f32 v[218:219], v[130:131], v[232:233], v[218:219] op_sel_hi:[0,1,1]
	v_cvt_pk_f32_fp8_sdwa v[232:233], v63 src0_sel:WORD_1
	v_pk_fma_f32 v[222:223], v[130:131], v[228:229], v[222:223] op_sel_hi:[0,1,1]
	v_pk_fma_f32 v[220:221], v[130:131], v[226:227], v[220:221] op_sel_hi:[0,1,1]
	v_pk_fma_f32 v[224:225], v[130:131], v[230:231], v[224:225] op_sel_hi:[0,1,1]
	v_pk_fma_f32 v[128:129], v[130:131], v[232:233], v[128:129] op_sel_hi:[0,1,1]
	s_and_b32 s98, s17, 0x700
	v_lshl_add_u32 v0, s98, 2, v189
	ds_read_b128 v[6:9], v0
	ds_read_b128 v[22:25], v0 offset:16
	ds_read_b128 v[38:41], v0 offset:32
	ds_read_b128 v[54:57], v0 offset:48
	v_permlane32_swap_b32 v134, v222
	v_permlane32_swap_b32 v135, v223
	v_permlane32_swap_b32 v132, v220
	v_permlane32_swap_b32 v133, v221
	v_permlane32_swap_b32 v216, v224
	v_permlane32_swap_b32 v217, v225
	v_permlane32_swap_b32 v218, v128
	v_permlane32_swap_b32 v219, v129
	v_pk_add_f32 v[130:131], v[132:133], v[220:221]
	v_pk_add_f32 v[132:133], v[134:135], v[222:223]
	v_pk_add_f32 v[134:135], v[216:217], v[224:225]
	v_pk_add_f32 v[128:129], v[218:219], v[128:129]
	s_nop 1
	v_permlane16_swap_b32 v130, v134
	v_permlane16_swap_b32 v131, v135
	v_permlane16_swap_b32 v132, v128
	v_permlane16_swap_b32 v133, v129
	v_pk_add_f32 v[130:131], v[130:131], v[134:135]
	v_pk_add_f32 v[132:133], v[132:133], v[128:129]
	s_cmp_lg_u32 s1, 0
	s_nop 1
	v_add_f32_dpp v128, v130, v130 row_ror:8 row_mask:0xf bank_mask:0x3
	v_add_f32_dpp v128, v132, v132 row_ror:8 row_mask:0xf bank_mask:0xc
	v_add_f32_dpp v129, v131, v131 row_ror:8 row_mask:0xf bank_mask:0x3
	v_add_f32_dpp v129, v133, v133 row_ror:8 row_mask:0xf bank_mask:0xc
	v_lshlrev_b32_e32 v138, 2, v214
	s_cbranch_scc1 .LBB0_936
	global_load_dwordx2 v[178:179], v138, s[46:47]
	global_load_dwordx2 v[180:181], v138, s[48:49]
.LBB0_936:
	s_waitcnt lgkmcnt(0)
	v_lshlrev_b32_e32 v132, 16, v210
	v_and_b32_e32 v133, 0xffff0000, v210
	v_lshlrev_b32_e32 v134, 16, v211
	v_and_b32_e32 v135, 0xffff0000, v211
	v_readlane_b32 s98, v248, s1
	v_readlane_b32 s99, v249, s1
	v_or_b32_e32 v214, s1, v176
	s_waitcnt lgkmcnt(0)
	ds_bpermute_b32 v128, v250, v128
	ds_bpermute_b32 v129, v250, v129
	v_pk_fma_f32 v[130:131], v[132:133], s[74:75], v[134:135] op_sel_hi:[1,0,1]
	v_ashrrev_i32_e32 v215, 31, v214
	v_pk_add_f32 v[130:131], v[130:131], s[98:99] op_sel_hi:[1,0] neg_lo:[0,1] neg_hi:[0,1]
	s_add_i32 s61, s0, 2
	v_lshlrev_b64 v[214:215], 13, v[214:215]
	v_pk_mul_f32 v[130:131], s[98:99], v[130:131] op_sel:[1,0]
	s_cmpk_gt_u32 s0, 0xfd
	v_lshl_add_u64 v[214:215], s[78:79], 0, v[214:215]
	s_waitcnt vmcnt(0)
	v_pk_fma_f32 v[130:131], v[130:131], v[178:179], v[180:181]
	s_cselect_b64 s[0:1], -1, 0
	v_lshl_add_u64 v[214:215], v[214:215], 0, v[138:139]
	s_waitcnt lgkmcnt(0)
	v_pk_fma_f32 v[128:129], v[130:131], s[74:75], v[128:129] op_sel_hi:[1,0,1]
	s_and_b64 vcc, exec, s[0:1]
	global_store_dwordx2 v[214:215], v[128:129], off nt
	s_cbranch_vccnz .LBB0_933
	s_and_b32 s14, s34, 0x3e00000
	s_add_u32 s14, s38, s14
	s_waitcnt lgkmcnt(2)
	s_waitcnt lgkmcnt(1)
	s_waitcnt lgkmcnt(0)
	s_addc_u32 s15, s39, 0
	v_lshl_or_b32 v4, v7, 7, v137
	v_lshl_or_b32 v0, v6, 7, v174
	v_lshl_or_b32 v12, v9, 7, v137
	v_lshl_or_b32 v8, v8, 7, v174
	v_lshl_or_b32 v20, v23, 7, v137
	v_lshl_or_b32 v16, v22, 7, v174
	v_lshl_or_b32 v28, v25, 7, v137
	v_lshl_or_b32 v24, v24, 7, v174
	v_lshl_or_b32 v36, v39, 7, v137
	v_lshl_or_b32 v32, v38, 7, v174
	v_lshl_or_b32 v44, v41, 7, v137
	v_lshl_or_b32 v40, v40, 7, v174
	v_lshl_or_b32 v52, v55, 7, v137
	v_lshl_or_b32 v48, v54, 7, v174
	v_lshl_or_b32 v60, v57, 7, v137
	v_lshl_or_b32 v56, v56, 7, v174
	global_load_dwordx4 v[0:3], v0, s[14:15]
	s_nop 0
	global_load_dwordx4 v[4:7], v4, s[14:15]
	s_nop 0
	global_load_dwordx4 v[8:11], v8, s[14:15]
	s_nop 0
	global_load_dwordx4 v[12:15], v12, s[14:15]
	s_nop 0
	global_load_dwordx4 v[16:19], v16, s[14:15]
	s_nop 0
	global_load_dwordx4 v[20:23], v20, s[14:15]
	s_nop 0
	global_load_dwordx4 v[24:27], v24, s[14:15]
	s_nop 0
	global_load_dwordx4 v[28:31], v28, s[14:15]
	s_nop 0
	global_load_dwordx4 v[32:35], v32, s[14:15]
	s_nop 0
	global_load_dwordx4 v[36:39], v36, s[14:15]
	s_nop 0
	global_load_dwordx4 v[40:43], v40, s[14:15]
	s_nop 0
	global_load_dwordx4 v[44:47], v44, s[14:15]
	s_nop 0
	global_load_dwordx4 v[48:51], v48, s[14:15]
	s_nop 0
	global_load_dwordx4 v[52:55], v52, s[14:15]
	s_nop 0
	global_load_dwordx4 v[56:59], v56, s[14:15]
	s_nop 0
	global_load_dwordx4 v[60:63], v60, s[14:15]
	s_branch .LBB0_933
